# KV-cache bf16 copy loop x2 on top of first_rows/sb_gemv prefetch (without the final-norm change)
# baseline (speedup 1.0000x reference)
.LBB0_94:
	v_lshlrev_b32_e32 v0, 4, v2
	v_and_b32_e32 v9, 0x7fff8, v3
	v_and_b32_e32 v18, 0x700000, v0
	v_cmp_lt_i32_e32 vcc, s3, v2
	v_or_b32_e32 v0, v18, v9
	v_lshlrev_b32_e32 v0, 2, v0
	v_cndmask_b32_e32 v11, v4, v5, vcc
	v_cndmask_b32_e32 v10, v6, v7, vcc
	v_lshl_add_u64 v[20:21], v[10:11], 0, v[0:1]
	global_load_dwordx4 v[10:13], v[20:21], off
	global_load_dwordx4 v[14:17], v[20:21], off offset:16
	v_cndmask_b32_e32 v0, 0, v8, vcc
	v_mov_b32_e32 v19, v1
	v_add_u32_e32 v2, s48, v2
	v_lshl_add_u64 v[20:21], s[8:9], 0, v[0:1]
	v_lshlrev_b32_e32 v0, 1, v9
	v_lshl_add_u64 v[18:19], v[20:21], 0, v[18:19]
	v_add_u32_e32 v3, s2, v3
	v_lshl_add_u64 v[18:19], v[18:19], 0, v[0:1]
	v_lshlrev_b32_e32 v70, 4, v2
	v_and_b32_e32 v72, 0x7fff8, v3
	v_and_b32_e32 v74, 0x700000, v70
	v_cmp_lt_i32_e32 vcc, s3, v2
	v_or_b32_e32 v70, v74, v72
	v_lshlrev_b32_e32 v70, 2, v70
	v_cndmask_b32_e32 v79, v4, v5, vcc
	v_cndmask_b32_e32 v78, v6, v7, vcc
	v_mov_b32_e32 v71, 0
	v_lshl_add_u64 v[76:77], v[78:79], 0, v[70:71]
	global_load_dwordx4 v[78:81], v[76:77], off
	global_load_dwordx4 v[82:85], v[76:77], off offset:16
	v_cndmask_b32_e32 v70, 0, v8, vcc
	v_mov_b32_e32 v75, v1
	v_add_u32_e32 v2, s48, v2
	v_lshl_add_u64 v[76:77], s[8:9], 0, v[70:71]
	v_cmp_lt_i32_e64 s[4:5], s12, v2
	v_lshlrev_b32_e32 v70, 1, v72
	v_lshl_add_u64 v[74:75], v[76:77], 0, v[74:75]
	v_add_u32_e32 v3, s2, v3
	s_or_b64 s[10:11], s[4:5], s[10:11]
	v_lshl_add_u64 v[74:75], v[74:75], 0, v[70:71]
	s_waitcnt vmcnt(3)
	v_cvt_pk_bf16_f32 v10, v10, v11
	v_cvt_pk_bf16_f32 v11, v12, v13
	s_waitcnt vmcnt(2)
	v_cvt_pk_bf16_f32 v12, v14, v15
	v_cvt_pk_bf16_f32 v13, v16, v17
	global_store_dwordx4 v[18:19], v[10:13], off
	s_waitcnt vmcnt(2)
	v_cvt_pk_bf16_f32 v78, v78, v79
	v_cvt_pk_bf16_f32 v79, v80, v81
	s_waitcnt vmcnt(1)
	v_cvt_pk_bf16_f32 v80, v82, v83
	v_cvt_pk_bf16_f32 v81, v84, v85
	global_store_dwordx4 v[74:75], v[78:81], off
	s_andn2_b64 exec, exec, s[10:11]
	s_cbranch_execnz .LBB0_94
